# K-loop: barrier B moved 2 MFMAs earlier in each MFMA segment
# baseline (speedup 1.0000x reference)
.LBB0_390:
	s_add_u32 s38, s42, 0x100
	s_addc_u32 s39, s43, 0
	s_add_i32 s4, 0, 0x10000
	s_cmp_eq_u32 s73, 12
	s_cselect_b32 s69, s29, s39
	s_cselect_b32 s68, vcc_lo, s38
	s_cselect_b32 s67, s37, s72
	s_cselect_b32 s66, vcc_hi, s59
	s_add_i32 s6, 0, 0x14000
	v_add_u32_e32 v142, s4, v251
	v_add_u32_e32 v158, s6, v251
	ds_read_b128 v[130:133], v142
	ds_read_b128 v[134:137], v142 offset:1024
	ds_read_b128 v[138:141], v142 offset:2048
	ds_read_b128 v[142:145], v142 offset:3072
	ds_read_b128 v[146:149], v158
	ds_read_b128 v[150:153], v158 offset:1024
	ds_read_b128 v[154:157], v158 offset:2048
	ds_read_b128 v[158:161], v158 offset:3072
	v_lshl_add_u64 v[194:195], s[42:43], 0, v[228:229]
	s_add_i32 m0, s75, 0xc000
	ds_read_b128 v[162:165], v244
	ds_read_b128 v[166:169], v244 offset:1024
	ds_read_b128 v[170:173], v244 offset:2048
	ds_read_b128 v[174:177], v244 offset:3072
	ds_read_b128 v[178:181], v244 offset:4096
	ds_read_b128 v[182:185], v244 offset:5120
	ds_read_b128 v[186:189], v244 offset:6144
	ds_read_b128 v[190:193], v244 offset:7168
	global_load_lds_dwordx4 v[194:195], off
	v_lshl_add_u64 v[194:195], s[42:43], 0, v[230:231]
	s_add_i32 m0, s75, 0xe000
	s_nop 0
	global_load_lds_dwordx4 v[194:195], off
	s_waitcnt vmcnt(8)
	s_waitcnt lgkmcnt(0)
	s_barrier
	s_setprio 1
	s_waitcnt lgkmcnt(0)
	v_mfma_f32_16x16x32_bf16 v[114:117], v[130:133], v[162:165], v[114:117]
	v_mfma_f32_16x16x32_bf16 v[122:125], v[138:141], v[162:165], v[122:125]
	v_mfma_f32_16x16x32_bf16 v[118:121], v[130:133], v[170:173], v[118:121]
	v_mfma_f32_16x16x32_bf16 v[126:129], v[138:141], v[170:173], v[126:129]
	v_mfma_f32_16x16x32_bf16 v[54:57], v[130:133], v[178:181], v[54:57]
	v_mfma_f32_16x16x32_bf16 v[70:73], v[138:141], v[178:181], v[70:73]
	v_mfma_f32_16x16x32_bf16 v[50:53], v[130:133], v[186:189], v[50:53]
	v_mfma_f32_16x16x32_bf16 v[66:69], v[138:141], v[186:189], v[66:69]
	v_mfma_f32_16x16x32_bf16 v[114:117], v[134:137], v[166:169], v[114:117]
	v_mfma_f32_16x16x32_bf16 v[122:125], v[142:145], v[166:169], v[122:125]
	v_mfma_f32_16x16x32_bf16 v[118:121], v[134:137], v[174:177], v[118:121]
	v_mfma_f32_16x16x32_bf16 v[126:129], v[142:145], v[174:177], v[126:129]
	v_mfma_f32_16x16x32_bf16 v[54:57], v[134:137], v[182:185], v[54:57]
	v_mfma_f32_16x16x32_bf16 v[70:73], v[142:145], v[182:185], v[70:73]
	v_mfma_f32_16x16x32_bf16 v[50:53], v[134:137], v[190:193], v[50:53]
	v_mfma_f32_16x16x32_bf16 v[66:69], v[142:145], v[190:193], v[66:69]
	s_setprio 0
	s_setprio 1
	v_mfma_f32_16x16x32_bf16 v[106:109], v[146:149], v[162:165], v[106:109]
	v_mfma_f32_16x16x32_bf16 v[42:45], v[154:157], v[162:165], v[42:45]
	v_mfma_f32_16x16x32_bf16 v[110:113], v[146:149], v[170:173], v[110:113]
	v_mfma_f32_16x16x32_bf16 v[46:49], v[154:157], v[170:173], v[46:49]
	v_mfma_f32_16x16x32_bf16 v[30:33], v[146:149], v[178:181], v[30:33]
	v_mfma_f32_16x16x32_bf16 v[14:17], v[154:157], v[178:181], v[14:17]
	v_mfma_f32_16x16x32_bf16 v[26:29], v[146:149], v[186:189], v[26:29]
	v_mfma_f32_16x16x32_bf16 v[10:13], v[154:157], v[186:189], v[10:13]
	v_mfma_f32_16x16x32_bf16 v[106:109], v[150:153], v[166:169], v[106:109]
	v_mfma_f32_16x16x32_bf16 v[42:45], v[158:161], v[166:169], v[42:45]
	v_mfma_f32_16x16x32_bf16 v[110:113], v[150:153], v[174:177], v[110:113]
	v_mfma_f32_16x16x32_bf16 v[46:49], v[158:161], v[174:177], v[46:49]
	v_mfma_f32_16x16x32_bf16 v[30:33], v[150:153], v[182:185], v[30:33]
	v_mfma_f32_16x16x32_bf16 v[14:17], v[158:161], v[182:185], v[14:17]
	s_barrier
	v_mfma_f32_16x16x32_bf16 v[26:29], v[150:153], v[190:193], v[26:29]
	v_mfma_f32_16x16x32_bf16 v[10:13], v[158:161], v[190:193], v[10:13]
	s_setprio 0
	s_add_i32 s4, s4, s74
	v_lshl_add_u64 v[194:195], s[66:67], 0, v[0:1]
	s_mov_b32 m0, s4
	ds_read_b128 v[162:165], v244 offset:16384
	ds_read_b128 v[166:169], v244 offset:17408
	ds_read_b128 v[170:173], v244 offset:18432
	ds_read_b128 v[174:177], v244 offset:19456
	ds_read_b128 v[178:181], v244 offset:20480
	ds_read_b128 v[182:185], v244 offset:21504
	ds_read_b128 v[186:189], v244 offset:22528
	ds_read_b128 v[190:193], v244 offset:23552
	global_load_lds_dwordx4 v[194:195], off
	s_add_i32 m0, s4, 0x2000
	s_add_u32 s4, s66, 0x40000
	v_lshl_add_u64 v[196:197], s[66:67], 0, v[224:225]
	s_addc_u32 s5, s67, 0
	s_add_i32 s6, s6, s74
	global_load_lds_dwordx4 v[196:197], off
	v_lshl_add_u64 v[198:199], s[4:5], 0, v[0:1]
	s_mov_b32 m0, s6
	v_lshl_add_u64 v[200:201], s[68:69], 0, v[222:223]
	global_load_lds_dwordx4 v[198:199], off
	v_lshl_add_u64 v[198:199], s[4:5], 0, v[224:225]
	s_add_i32 m0, s6, 0x2000
	s_nop 0
	global_load_lds_dwordx4 v[198:199], off
	v_lshl_add_u64 v[198:199], s[68:69], 0, v[226:227]
	s_mov_b32 m0, s75
	s_nop 0
	global_load_lds_dwordx4 v[198:199], off
	s_mov_b32 m0, s76
	s_nop 0
	global_load_lds_dwordx4 v[200:201], off
	s_waitcnt vmcnt(8)
	s_waitcnt lgkmcnt(0)
	s_barrier
	s_setprio 1
	s_waitcnt lgkmcnt(0)
	v_mfma_f32_16x16x32_bf16 v[38:41], v[130:133], v[162:165], v[38:41]
	v_mfma_f32_16x16x32_bf16 v[62:65], v[138:141], v[162:165], v[62:65]
	v_mfma_f32_16x16x32_bf16 v[34:37], v[130:133], v[170:173], v[34:37]
	v_mfma_f32_16x16x32_bf16 v[58:61], v[138:141], v[170:173], v[58:61]
	v_mfma_f32_16x16x32_bf16 v[102:105], v[130:133], v[178:181], v[102:105]
	v_mfma_f32_16x16x32_bf16 v[98:101], v[138:141], v[178:181], v[98:101]
	v_mfma_f32_16x16x32_bf16 v[94:97], v[130:133], v[186:189], v[94:97]
	v_mfma_f32_16x16x32_bf16 v[90:93], v[138:141], v[186:189], v[90:93]
	v_mfma_f32_16x16x32_bf16 v[38:41], v[134:137], v[166:169], v[38:41]
	v_mfma_f32_16x16x32_bf16 v[62:65], v[142:145], v[166:169], v[62:65]
	v_mfma_f32_16x16x32_bf16 v[34:37], v[134:137], v[174:177], v[34:37]
	v_mfma_f32_16x16x32_bf16 v[58:61], v[142:145], v[174:177], v[58:61]
	v_mfma_f32_16x16x32_bf16 v[102:105], v[134:137], v[182:185], v[102:105]
	v_mfma_f32_16x16x32_bf16 v[98:101], v[142:145], v[182:185], v[98:101]
	v_mfma_f32_16x16x32_bf16 v[94:97], v[134:137], v[190:193], v[94:97]
	v_mfma_f32_16x16x32_bf16 v[90:93], v[142:145], v[190:193], v[90:93]
	s_setprio 0
	s_setprio 1
	v_mfma_f32_16x16x32_bf16 v[22:25], v[146:149], v[162:165], v[22:25]
	v_mfma_f32_16x16x32_bf16 v[6:9], v[154:157], v[162:165], v[6:9]
	v_mfma_f32_16x16x32_bf16 v[18:21], v[146:149], v[170:173], v[18:21]
	v_mfma_f32_16x16x32_bf16 v[2:5], v[154:157], v[170:173], v[2:5]
	v_mfma_f32_16x16x32_bf16 v[86:89], v[146:149], v[178:181], v[86:89]
	v_mfma_f32_16x16x32_bf16 v[82:85], v[154:157], v[178:181], v[82:85]
	v_mfma_f32_16x16x32_bf16 v[78:81], v[146:149], v[186:189], v[78:81]
	v_mfma_f32_16x16x32_bf16 v[74:77], v[154:157], v[186:189], v[74:77]
	v_mfma_f32_16x16x32_bf16 v[22:25], v[150:153], v[166:169], v[22:25]
	v_mfma_f32_16x16x32_bf16 v[6:9], v[158:161], v[166:169], v[6:9]
	v_mfma_f32_16x16x32_bf16 v[18:21], v[150:153], v[174:177], v[18:21]
	v_mfma_f32_16x16x32_bf16 v[2:5], v[158:161], v[174:177], v[2:5]
	v_mfma_f32_16x16x32_bf16 v[86:89], v[150:153], v[182:185], v[86:89]
	v_mfma_f32_16x16x32_bf16 v[82:85], v[158:161], v[182:185], v[82:85]
	s_barrier
	v_mfma_f32_16x16x32_bf16 v[78:81], v[150:153], v[190:193], v[78:81]
	v_mfma_f32_16x16x32_bf16 v[74:77], v[158:161], v[190:193], v[74:77]
	s_setprio 0
	s_add_i32 s6, 0, 0x18000
	s_add_i32 s7, 0, 0x1c000
	v_add_u32_e32 v142, s6, v251
	v_add_u32_e32 v158, s7, v251
	ds_read_b128 v[130:133], v142
	ds_read_b128 v[134:137], v142 offset:1024
	ds_read_b128 v[138:141], v142 offset:2048
	ds_read_b128 v[142:145], v142 offset:3072
	ds_read_b128 v[146:149], v158
	ds_read_b128 v[150:153], v158 offset:1024
	ds_read_b128 v[154:157], v158 offset:2048
	ds_read_b128 v[158:161], v158 offset:3072
	s_add_u32 s4, s68, 0x2000
	s_addc_u32 s5, s69, 0
	s_mov_b32 m0, s77
	v_lshl_add_u64 v[202:203], s[4:5], 0, v[226:227]
	ds_read_b128 v[162:165], v244 offset:32768
	ds_read_b128 v[166:169], v244 offset:33792
	ds_read_b128 v[170:173], v244 offset:34816
	ds_read_b128 v[174:177], v244 offset:35840
	ds_read_b128 v[178:181], v244 offset:36864
	ds_read_b128 v[182:185], v244 offset:37888
	ds_read_b128 v[186:189], v244 offset:38912
	ds_read_b128 v[190:193], v244 offset:39936
	global_load_lds_dwordx4 v[202:203], off
	v_lshl_add_u64 v[202:203], s[4:5], 0, v[222:223]
	s_mov_b32 m0, s78
	s_nop 0
	global_load_lds_dwordx4 v[202:203], off
	s_waitcnt vmcnt(8)
	s_waitcnt lgkmcnt(0)
	s_barrier
	s_setprio 1
	s_waitcnt lgkmcnt(0)
	v_mfma_f32_16x16x32_bf16 v[114:117], v[130:133], v[162:165], v[114:117]
	v_mfma_f32_16x16x32_bf16 v[122:125], v[138:141], v[162:165], v[122:125]
	v_mfma_f32_16x16x32_bf16 v[118:121], v[130:133], v[170:173], v[118:121]
	v_mfma_f32_16x16x32_bf16 v[126:129], v[138:141], v[170:173], v[126:129]
	v_mfma_f32_16x16x32_bf16 v[54:57], v[130:133], v[178:181], v[54:57]
	v_mfma_f32_16x16x32_bf16 v[70:73], v[138:141], v[178:181], v[70:73]
	v_mfma_f32_16x16x32_bf16 v[50:53], v[130:133], v[186:189], v[50:53]
	v_mfma_f32_16x16x32_bf16 v[66:69], v[138:141], v[186:189], v[66:69]
	v_mfma_f32_16x16x32_bf16 v[114:117], v[134:137], v[166:169], v[114:117]
	v_mfma_f32_16x16x32_bf16 v[122:125], v[142:145], v[166:169], v[122:125]
	v_mfma_f32_16x16x32_bf16 v[118:121], v[134:137], v[174:177], v[118:121]
	v_mfma_f32_16x16x32_bf16 v[126:129], v[142:145], v[174:177], v[126:129]
	v_mfma_f32_16x16x32_bf16 v[54:57], v[134:137], v[182:185], v[54:57]
	v_mfma_f32_16x16x32_bf16 v[70:73], v[142:145], v[182:185], v[70:73]
	v_mfma_f32_16x16x32_bf16 v[50:53], v[134:137], v[190:193], v[50:53]
	v_mfma_f32_16x16x32_bf16 v[66:69], v[142:145], v[190:193], v[66:69]
	s_setprio 0
	s_setprio 1
	v_mfma_f32_16x16x32_bf16 v[106:109], v[146:149], v[162:165], v[106:109]
	v_mfma_f32_16x16x32_bf16 v[42:45], v[154:157], v[162:165], v[42:45]
	v_mfma_f32_16x16x32_bf16 v[110:113], v[146:149], v[170:173], v[110:113]
	v_mfma_f32_16x16x32_bf16 v[46:49], v[154:157], v[170:173], v[46:49]
	v_mfma_f32_16x16x32_bf16 v[30:33], v[146:149], v[178:181], v[30:33]
	v_mfma_f32_16x16x32_bf16 v[14:17], v[154:157], v[178:181], v[14:17]
	v_mfma_f32_16x16x32_bf16 v[26:29], v[146:149], v[186:189], v[26:29]
	v_mfma_f32_16x16x32_bf16 v[10:13], v[154:157], v[186:189], v[10:13]
	v_mfma_f32_16x16x32_bf16 v[106:109], v[150:153], v[166:169], v[106:109]
	v_mfma_f32_16x16x32_bf16 v[42:45], v[158:161], v[166:169], v[42:45]
	v_mfma_f32_16x16x32_bf16 v[110:113], v[150:153], v[174:177], v[110:113]
	v_mfma_f32_16x16x32_bf16 v[46:49], v[158:161], v[174:177], v[46:49]
	v_mfma_f32_16x16x32_bf16 v[30:33], v[150:153], v[182:185], v[30:33]
	v_mfma_f32_16x16x32_bf16 v[14:17], v[158:161], v[182:185], v[14:17]
	s_barrier
	v_mfma_f32_16x16x32_bf16 v[26:29], v[150:153], v[190:193], v[26:29]
	v_mfma_f32_16x16x32_bf16 v[10:13], v[158:161], v[190:193], v[10:13]
	s_setprio 0
	s_add_i32 s4, s6, s74
	v_lshl_add_u64 v[194:195], v[194:195], 0, s[82:83]
	s_mov_b32 m0, s4
	ds_read_b128 v[162:165], v244 offset:49152
	ds_read_b128 v[166:169], v244 offset:50176
	ds_read_b128 v[170:173], v244 offset:51200
	ds_read_b128 v[174:177], v244 offset:52224
	ds_read_b128 v[178:181], v244 offset:53248
	ds_read_b128 v[182:185], v244 offset:54272
	ds_read_b128 v[186:189], v244 offset:55296
	ds_read_b128 v[190:193], v244 offset:56320
	global_load_lds_dwordx4 v[194:195], off
	s_add_i32 m0, s4, 0x2000
	s_add_u32 s4, s66, 0x40080
	v_lshl_add_u64 v[194:195], v[196:197], 0, s[82:83]
	s_addc_u32 s5, s67, 0
	s_add_i32 s6, s7, s74
	global_load_lds_dwordx4 v[194:195], off
	v_lshl_add_u64 v[194:195], s[4:5], 0, v[0:1]
	s_mov_b32 m0, s6
	s_nop 0
	global_load_lds_dwordx4 v[194:195], off
	v_lshl_add_u64 v[194:195], s[4:5], 0, v[224:225]
	s_add_i32 m0, s6, 0x2000
	s_nop 0
	global_load_lds_dwordx4 v[194:195], off
	v_lshl_add_u64 v[194:195], v[198:199], 0, s[82:83]
	s_mov_b32 m0, s94
	s_nop 0
	global_load_lds_dwordx4 v[194:195], off
	v_lshl_add_u64 v[194:195], v[200:201], 0, s[82:83]
	s_mov_b32 m0, s95
	s_nop 0
	global_load_lds_dwordx4 v[194:195], off
	s_waitcnt vmcnt(8)
	s_waitcnt lgkmcnt(0)
	s_barrier
	s_setprio 1
	s_waitcnt lgkmcnt(0)
	v_mfma_f32_16x16x32_bf16 v[38:41], v[130:133], v[162:165], v[38:41]
	v_mfma_f32_16x16x32_bf16 v[62:65], v[138:141], v[162:165], v[62:65]
	v_mfma_f32_16x16x32_bf16 v[34:37], v[130:133], v[170:173], v[34:37]
	v_mfma_f32_16x16x32_bf16 v[58:61], v[138:141], v[170:173], v[58:61]
	v_mfma_f32_16x16x32_bf16 v[102:105], v[130:133], v[178:181], v[102:105]
	v_mfma_f32_16x16x32_bf16 v[98:101], v[138:141], v[178:181], v[98:101]
	v_mfma_f32_16x16x32_bf16 v[94:97], v[130:133], v[186:189], v[94:97]
	v_mfma_f32_16x16x32_bf16 v[90:93], v[138:141], v[186:189], v[90:93]
	v_mfma_f32_16x16x32_bf16 v[38:41], v[134:137], v[166:169], v[38:41]
	v_mfma_f32_16x16x32_bf16 v[62:65], v[142:145], v[166:169], v[62:65]
	v_mfma_f32_16x16x32_bf16 v[34:37], v[134:137], v[174:177], v[34:37]
	v_mfma_f32_16x16x32_bf16 v[58:61], v[142:145], v[174:177], v[58:61]
	v_mfma_f32_16x16x32_bf16 v[102:105], v[134:137], v[182:185], v[102:105]
	v_mfma_f32_16x16x32_bf16 v[98:101], v[142:145], v[182:185], v[98:101]
	v_mfma_f32_16x16x32_bf16 v[94:97], v[134:137], v[190:193], v[94:97]
	v_mfma_f32_16x16x32_bf16 v[90:93], v[142:145], v[190:193], v[90:93]
	s_setprio 0
	s_setprio 1
	v_mfma_f32_16x16x32_bf16 v[22:25], v[146:149], v[162:165], v[22:25]
	v_mfma_f32_16x16x32_bf16 v[6:9], v[154:157], v[162:165], v[6:9]
	v_mfma_f32_16x16x32_bf16 v[18:21], v[146:149], v[170:173], v[18:21]
	v_mfma_f32_16x16x32_bf16 v[2:5], v[154:157], v[170:173], v[2:5]
	v_mfma_f32_16x16x32_bf16 v[86:89], v[146:149], v[178:181], v[86:89]
	v_mfma_f32_16x16x32_bf16 v[82:85], v[154:157], v[178:181], v[82:85]
	v_mfma_f32_16x16x32_bf16 v[78:81], v[146:149], v[186:189], v[78:81]
	v_mfma_f32_16x16x32_bf16 v[74:77], v[154:157], v[186:189], v[74:77]
	v_mfma_f32_16x16x32_bf16 v[22:25], v[150:153], v[166:169], v[22:25]
	v_mfma_f32_16x16x32_bf16 v[6:9], v[158:161], v[166:169], v[6:9]
	v_mfma_f32_16x16x32_bf16 v[18:21], v[150:153], v[174:177], v[18:21]
	v_mfma_f32_16x16x32_bf16 v[2:5], v[158:161], v[174:177], v[2:5]
	v_mfma_f32_16x16x32_bf16 v[86:89], v[150:153], v[182:185], v[86:89]
	v_mfma_f32_16x16x32_bf16 v[82:85], v[158:161], v[182:185], v[82:85]
	s_barrier
	v_mfma_f32_16x16x32_bf16 v[78:81], v[150:153], v[190:193], v[78:81]
	v_mfma_f32_16x16x32_bf16 v[74:77], v[158:161], v[190:193], v[74:77]
	s_setprio 0
	s_add_i32 s73, s73, 2
	s_add_u32 s59, s59, 0x100
	s_addc_u32 s72, s72, 0
	s_cmp_gt_u32 s73, 13
	s_mov_b64 s[42:43], s[38:39]
	s_cbranch_scc0 .LBB0_390
	s_and_b64 vcc, exec, s[50:51]
	s_cbranch_vccz .LBB0_393
	s_barrier

.LBB0_452:
	s_add_i32 s59, s34, 2
	s_add_u32 s4, s30, 0x80
	s_addc_u32 s5, s31, 0
	s_add_i32 s6, 0, 0x10000
	s_cmp_eq_u32 s53, s34
	s_cselect_b32 s35, s27, s5
	s_cselect_b32 s34, s26, s4
	s_cselect_b32 s5, s29, s43
	s_cselect_b32 s4, s28, s42
	s_add_i32 s7, 0, 0x14000
	v_add_u32_e32 v142, s6, v184
	v_add_u32_e32 v168, s7, v184
	ds_read_b128 v[130:133], v142
	ds_read_b128 v[134:137], v142 offset:1024
	ds_read_b128 v[138:141], v142 offset:2048
	ds_read_b128 v[142:145], v142 offset:3072
	ds_read_b128 v[146:149], v168
	ds_read_b128 v[150:153], v168 offset:1024
	ds_read_b128 v[154:157], v168 offset:2048
	ds_read_b128 v[168:171], v168 offset:3072
	v_lshl_add_u64 v[180:181], s[30:31], 0, v[164:165]
	s_add_i32 m0, s38, 0xc000
	ds_read_b128 v[172:175], v187
	ds_read_b128 v[176:179], v187 offset:1024
	ds_read_b128 v[188:191], v187 offset:2048
	ds_read_b128 v[192:195], v187 offset:3072
	ds_read_b128 v[196:199], v187 offset:4096
	ds_read_b128 v[200:203], v187 offset:5120
	ds_read_b128 v[204:207], v187 offset:6144
	ds_read_b128 v[222:225], v187 offset:7168
	global_load_lds_dwordx4 v[180:181], off
	v_lshl_add_u64 v[180:181], s[30:31], 0, v[166:167]
	s_add_i32 m0, s38, 0xe000
	s_nop 0
	global_load_lds_dwordx4 v[180:181], off
	s_waitcnt vmcnt(8)
	s_waitcnt lgkmcnt(0)
	s_barrier
	s_setprio 1
	s_waitcnt lgkmcnt(0)
	v_mfma_f32_16x16x32_bf16 v[126:129], v[130:133], v[172:175], v[126:129]
	v_mfma_f32_16x16x32_bf16 v[122:125], v[138:141], v[172:175], v[122:125]
	v_mfma_f32_16x16x32_bf16 v[110:113], v[130:133], v[188:191], v[110:113]
	v_mfma_f32_16x16x32_bf16 v[106:109], v[138:141], v[188:191], v[106:109]
	v_mfma_f32_16x16x32_bf16 v[98:101], v[130:133], v[196:199], v[98:101]
	v_mfma_f32_16x16x32_bf16 v[90:93], v[138:141], v[196:199], v[90:93]
	v_mfma_f32_16x16x32_bf16 v[82:85], v[130:133], v[204:207], v[82:85]
	v_mfma_f32_16x16x32_bf16 v[74:77], v[138:141], v[204:207], v[74:77]
	v_mfma_f32_16x16x32_bf16 v[126:129], v[134:137], v[176:179], v[126:129]
	v_mfma_f32_16x16x32_bf16 v[122:125], v[142:145], v[176:179], v[122:125]
	v_mfma_f32_16x16x32_bf16 v[110:113], v[134:137], v[192:195], v[110:113]
	v_mfma_f32_16x16x32_bf16 v[106:109], v[142:145], v[192:195], v[106:109]
	v_mfma_f32_16x16x32_bf16 v[98:101], v[134:137], v[200:203], v[98:101]
	v_mfma_f32_16x16x32_bf16 v[90:93], v[142:145], v[200:203], v[90:93]
	v_mfma_f32_16x16x32_bf16 v[82:85], v[134:137], v[222:225], v[82:85]
	v_mfma_f32_16x16x32_bf16 v[74:77], v[142:145], v[222:225], v[74:77]
	s_setprio 0
	s_setprio 1
	v_mfma_f32_16x16x32_bf16 v[118:121], v[146:149], v[172:175], v[118:121]
	v_mfma_f32_16x16x32_bf16 v[114:117], v[154:157], v[172:175], v[114:117]
	v_mfma_f32_16x16x32_bf16 v[102:105], v[146:149], v[188:191], v[102:105]
	v_mfma_f32_16x16x32_bf16 v[94:97], v[154:157], v[188:191], v[94:97]
	v_mfma_f32_16x16x32_bf16 v[86:89], v[146:149], v[196:199], v[86:89]
	v_mfma_f32_16x16x32_bf16 v[78:81], v[154:157], v[196:199], v[78:81]
	v_mfma_f32_16x16x32_bf16 v[70:73], v[146:149], v[204:207], v[70:73]
	v_mfma_f32_16x16x32_bf16 v[66:69], v[154:157], v[204:207], v[66:69]
	v_mfma_f32_16x16x32_bf16 v[118:121], v[150:153], v[176:179], v[118:121]
	v_mfma_f32_16x16x32_bf16 v[114:117], v[168:171], v[176:179], v[114:117]
	v_mfma_f32_16x16x32_bf16 v[102:105], v[150:153], v[192:195], v[102:105]
	v_mfma_f32_16x16x32_bf16 v[94:97], v[168:171], v[192:195], v[94:97]
	v_mfma_f32_16x16x32_bf16 v[86:89], v[150:153], v[200:203], v[86:89]
	v_mfma_f32_16x16x32_bf16 v[78:81], v[168:171], v[200:203], v[78:81]
	s_barrier
	v_mfma_f32_16x16x32_bf16 v[70:73], v[150:153], v[222:225], v[70:73]
	v_mfma_f32_16x16x32_bf16 v[66:69], v[168:171], v[222:225], v[66:69]
	s_setprio 0
	s_add_i32 s6, s6, s37
	v_lshl_add_u64 v[180:181], s[4:5], 0, v[0:1]
	s_mov_b32 m0, s6
	ds_read_b128 v[172:175], v187 offset:16384
	ds_read_b128 v[176:179], v187 offset:17408
	ds_read_b128 v[188:191], v187 offset:18432
	ds_read_b128 v[192:195], v187 offset:19456
	ds_read_b128 v[196:199], v187 offset:20480
	ds_read_b128 v[200:203], v187 offset:21504
	ds_read_b128 v[204:207], v187 offset:22528
	ds_read_b128 v[222:225], v187 offset:23552
	global_load_lds_dwordx4 v[180:181], off
	s_add_i32 m0, s6, 0x2000
	v_lshl_add_u64 v[208:209], s[4:5], 0, v[160:161]
	s_add_u32 s4, s4, s84
	s_addc_u32 s5, s5, 0
	s_add_i32 s6, s7, s37
	global_load_lds_dwordx4 v[208:209], off
	v_lshl_add_u64 v[226:227], s[4:5], 0, v[0:1]
	s_mov_b32 m0, s6
	v_lshl_add_u64 v[228:229], s[4:5], 0, v[160:161]
	global_load_lds_dwordx4 v[226:227], off
	s_add_i32 m0, s6, 0x2000
	v_lshl_add_u64 v[230:231], s[34:35], 0, v[162:163]
	global_load_lds_dwordx4 v[228:229], off
	s_mov_b32 m0, s38
	v_lshl_add_u64 v[232:233], s[34:35], 0, v[158:159]
	global_load_lds_dwordx4 v[230:231], off
	s_mov_b32 m0, s39
	s_nop 0
	global_load_lds_dwordx4 v[232:233], off
	s_waitcnt vmcnt(8)
	s_waitcnt lgkmcnt(0)
	s_barrier
	s_setprio 1
	s_waitcnt lgkmcnt(0)
	v_mfma_f32_16x16x32_bf16 v[62:65], v[130:133], v[172:175], v[62:65]
	v_mfma_f32_16x16x32_bf16 v[58:61], v[138:141], v[172:175], v[58:61]
	v_mfma_f32_16x16x32_bf16 v[46:49], v[130:133], v[188:191], v[46:49]
	v_mfma_f32_16x16x32_bf16 v[42:45], v[138:141], v[188:191], v[42:45]
	v_mfma_f32_16x16x32_bf16 v[34:37], v[130:133], v[196:199], v[34:37]
	v_mfma_f32_16x16x32_bf16 v[26:29], v[138:141], v[196:199], v[26:29]
	v_mfma_f32_16x16x32_bf16 v[18:21], v[130:133], v[204:207], v[18:21]
	v_mfma_f32_16x16x32_bf16 v[10:13], v[138:141], v[204:207], v[10:13]
	v_mfma_f32_16x16x32_bf16 v[62:65], v[134:137], v[176:179], v[62:65]
	v_mfma_f32_16x16x32_bf16 v[58:61], v[142:145], v[176:179], v[58:61]
	v_mfma_f32_16x16x32_bf16 v[46:49], v[134:137], v[192:195], v[46:49]
	v_mfma_f32_16x16x32_bf16 v[42:45], v[142:145], v[192:195], v[42:45]
	v_mfma_f32_16x16x32_bf16 v[34:37], v[134:137], v[200:203], v[34:37]
	v_mfma_f32_16x16x32_bf16 v[26:29], v[142:145], v[200:203], v[26:29]
	v_mfma_f32_16x16x32_bf16 v[18:21], v[134:137], v[222:225], v[18:21]
	v_mfma_f32_16x16x32_bf16 v[10:13], v[142:145], v[222:225], v[10:13]
	s_setprio 0
	s_setprio 1
	v_mfma_f32_16x16x32_bf16 v[54:57], v[146:149], v[172:175], v[54:57]
	v_mfma_f32_16x16x32_bf16 v[50:53], v[154:157], v[172:175], v[50:53]
	v_mfma_f32_16x16x32_bf16 v[38:41], v[146:149], v[188:191], v[38:41]
	v_mfma_f32_16x16x32_bf16 v[30:33], v[154:157], v[188:191], v[30:33]
	v_mfma_f32_16x16x32_bf16 v[22:25], v[146:149], v[196:199], v[22:25]
	v_mfma_f32_16x16x32_bf16 v[14:17], v[154:157], v[196:199], v[14:17]
	v_mfma_f32_16x16x32_bf16 v[6:9], v[146:149], v[204:207], v[6:9]
	v_mfma_f32_16x16x32_bf16 v[2:5], v[154:157], v[204:207], v[2:5]
	v_mfma_f32_16x16x32_bf16 v[54:57], v[150:153], v[176:179], v[54:57]
	v_mfma_f32_16x16x32_bf16 v[50:53], v[168:171], v[176:179], v[50:53]
	v_mfma_f32_16x16x32_bf16 v[38:41], v[150:153], v[192:195], v[38:41]
	v_mfma_f32_16x16x32_bf16 v[30:33], v[168:171], v[192:195], v[30:33]
	v_mfma_f32_16x16x32_bf16 v[22:25], v[150:153], v[200:203], v[22:25]
	v_mfma_f32_16x16x32_bf16 v[14:17], v[168:171], v[200:203], v[14:17]
	s_barrier
	v_mfma_f32_16x16x32_bf16 v[6:9], v[150:153], v[222:225], v[6:9]
	v_mfma_f32_16x16x32_bf16 v[2:5], v[168:171], v[222:225], v[2:5]
	s_setprio 0
	s_add_i32 s6, 0, 0x18000
	s_add_i32 s7, 0, 0x1c000
	v_add_u32_e32 v142, s6, v184
	v_add_u32_e32 v168, s7, v184
	ds_read_b128 v[130:133], v142
	ds_read_b128 v[134:137], v142 offset:1024
	ds_read_b128 v[138:141], v142 offset:2048
	ds_read_b128 v[142:145], v142 offset:3072
	ds_read_b128 v[146:149], v168
	ds_read_b128 v[150:153], v168 offset:1024
	ds_read_b128 v[154:157], v168 offset:2048
	ds_read_b128 v[168:171], v168 offset:3072
	s_add_u32 s4, s34, s84
	s_addc_u32 s5, s35, 0
	s_mov_b32 m0, s45
	v_lshl_add_u64 v[234:235], s[4:5], 0, v[162:163]
	ds_read_b128 v[172:175], v187 offset:32768
	ds_read_b128 v[176:179], v187 offset:33792
	ds_read_b128 v[188:191], v187 offset:34816
	ds_read_b128 v[192:195], v187 offset:35840
	ds_read_b128 v[196:199], v187 offset:36864
	ds_read_b128 v[200:203], v187 offset:37888
	ds_read_b128 v[204:207], v187 offset:38912
	ds_read_b128 v[222:225], v187 offset:39936
	global_load_lds_dwordx4 v[234:235], off
	v_lshl_add_u64 v[234:235], s[4:5], 0, v[158:159]
	s_mov_b32 m0, s46
	s_nop 0
	global_load_lds_dwordx4 v[234:235], off
	s_waitcnt vmcnt(8)
	s_waitcnt lgkmcnt(0)
	s_barrier
	s_setprio 1
	s_waitcnt lgkmcnt(0)
	v_mfma_f32_16x16x32_bf16 v[126:129], v[130:133], v[172:175], v[126:129]
	v_mfma_f32_16x16x32_bf16 v[122:125], v[138:141], v[172:175], v[122:125]
	v_mfma_f32_16x16x32_bf16 v[110:113], v[130:133], v[188:191], v[110:113]
	v_mfma_f32_16x16x32_bf16 v[106:109], v[138:141], v[188:191], v[106:109]
	v_mfma_f32_16x16x32_bf16 v[98:101], v[130:133], v[196:199], v[98:101]
	v_mfma_f32_16x16x32_bf16 v[90:93], v[138:141], v[196:199], v[90:93]
	v_mfma_f32_16x16x32_bf16 v[82:85], v[130:133], v[204:207], v[82:85]
	v_mfma_f32_16x16x32_bf16 v[74:77], v[138:141], v[204:207], v[74:77]
	v_mfma_f32_16x16x32_bf16 v[126:129], v[134:137], v[176:179], v[126:129]
	v_mfma_f32_16x16x32_bf16 v[122:125], v[142:145], v[176:179], v[122:125]
	v_mfma_f32_16x16x32_bf16 v[110:113], v[134:137], v[192:195], v[110:113]
	v_mfma_f32_16x16x32_bf16 v[106:109], v[142:145], v[192:195], v[106:109]
	v_mfma_f32_16x16x32_bf16 v[98:101], v[134:137], v[200:203], v[98:101]
	v_mfma_f32_16x16x32_bf16 v[90:93], v[142:145], v[200:203], v[90:93]
	v_mfma_f32_16x16x32_bf16 v[82:85], v[134:137], v[222:225], v[82:85]
	v_mfma_f32_16x16x32_bf16 v[74:77], v[142:145], v[222:225], v[74:77]
	s_setprio 0
	s_setprio 1
	v_mfma_f32_16x16x32_bf16 v[118:121], v[146:149], v[172:175], v[118:121]
	v_mfma_f32_16x16x32_bf16 v[114:117], v[154:157], v[172:175], v[114:117]
	v_mfma_f32_16x16x32_bf16 v[102:105], v[146:149], v[188:191], v[102:105]
	v_mfma_f32_16x16x32_bf16 v[94:97], v[154:157], v[188:191], v[94:97]
	v_mfma_f32_16x16x32_bf16 v[86:89], v[146:149], v[196:199], v[86:89]
	v_mfma_f32_16x16x32_bf16 v[78:81], v[154:157], v[196:199], v[78:81]
	v_mfma_f32_16x16x32_bf16 v[70:73], v[146:149], v[204:207], v[70:73]
	v_mfma_f32_16x16x32_bf16 v[66:69], v[154:157], v[204:207], v[66:69]
	v_mfma_f32_16x16x32_bf16 v[118:121], v[150:153], v[176:179], v[118:121]
	v_mfma_f32_16x16x32_bf16 v[114:117], v[168:171], v[176:179], v[114:117]
	v_mfma_f32_16x16x32_bf16 v[102:105], v[150:153], v[192:195], v[102:105]
	v_mfma_f32_16x16x32_bf16 v[94:97], v[168:171], v[192:195], v[94:97]
	v_mfma_f32_16x16x32_bf16 v[86:89], v[150:153], v[200:203], v[86:89]
	v_mfma_f32_16x16x32_bf16 v[78:81], v[168:171], v[200:203], v[78:81]
	s_barrier
	v_mfma_f32_16x16x32_bf16 v[70:73], v[150:153], v[222:225], v[70:73]
	v_mfma_f32_16x16x32_bf16 v[66:69], v[168:171], v[222:225], v[66:69]
	s_setprio 0
	s_add_i32 s4, s6, s37
	v_lshl_add_u64 v[180:181], v[180:181], 0, s[82:83]
	s_mov_b32 m0, s4
	ds_read_b128 v[172:175], v187 offset:49152
	ds_read_b128 v[176:179], v187 offset:50176
	ds_read_b128 v[188:191], v187 offset:51200
	ds_read_b128 v[192:195], v187 offset:52224
	ds_read_b128 v[196:199], v187 offset:53248
	ds_read_b128 v[200:203], v187 offset:54272
	ds_read_b128 v[204:207], v187 offset:55296
	ds_read_b128 v[222:225], v187 offset:56320
	global_load_lds_dwordx4 v[180:181], off
	v_lshl_add_u64 v[180:181], v[208:209], 0, s[82:83]
	s_add_i32 m0, s4, 0x2000
	s_add_i32 s4, s7, s37
	global_load_lds_dwordx4 v[180:181], off
	v_lshl_add_u64 v[180:181], v[226:227], 0, s[82:83]
	s_mov_b32 m0, s4
	s_nop 0
	global_load_lds_dwordx4 v[180:181], off
	v_lshl_add_u64 v[180:181], v[228:229], 0, s[82:83]
	s_add_i32 m0, s4, 0x2000
	s_nop 0
	global_load_lds_dwordx4 v[180:181], off
	v_lshl_add_u64 v[180:181], v[230:231], 0, s[82:83]
	s_mov_b32 m0, s51
	s_nop 0
	global_load_lds_dwordx4 v[180:181], off
	v_lshl_add_u64 v[180:181], v[232:233], 0, s[82:83]
	s_mov_b32 m0, s52
	s_nop 0
	global_load_lds_dwordx4 v[180:181], off
	s_waitcnt vmcnt(8)
	s_waitcnt lgkmcnt(0)
	s_barrier
	s_setprio 1
	s_waitcnt lgkmcnt(0)
	v_mfma_f32_16x16x32_bf16 v[62:65], v[130:133], v[172:175], v[62:65]
	v_mfma_f32_16x16x32_bf16 v[58:61], v[138:141], v[172:175], v[58:61]
	v_mfma_f32_16x16x32_bf16 v[46:49], v[130:133], v[188:191], v[46:49]
	v_mfma_f32_16x16x32_bf16 v[42:45], v[138:141], v[188:191], v[42:45]
	v_mfma_f32_16x16x32_bf16 v[34:37], v[130:133], v[196:199], v[34:37]
	v_mfma_f32_16x16x32_bf16 v[26:29], v[138:141], v[196:199], v[26:29]
	v_mfma_f32_16x16x32_bf16 v[18:21], v[130:133], v[204:207], v[18:21]
	v_mfma_f32_16x16x32_bf16 v[10:13], v[138:141], v[204:207], v[10:13]
	v_mfma_f32_16x16x32_bf16 v[62:65], v[134:137], v[176:179], v[62:65]
	v_mfma_f32_16x16x32_bf16 v[58:61], v[142:145], v[176:179], v[58:61]
	v_mfma_f32_16x16x32_bf16 v[46:49], v[134:137], v[192:195], v[46:49]
	v_mfma_f32_16x16x32_bf16 v[42:45], v[142:145], v[192:195], v[42:45]
	v_mfma_f32_16x16x32_bf16 v[34:37], v[134:137], v[200:203], v[34:37]
	v_mfma_f32_16x16x32_bf16 v[26:29], v[142:145], v[200:203], v[26:29]
	v_mfma_f32_16x16x32_bf16 v[18:21], v[134:137], v[222:225], v[18:21]
	v_mfma_f32_16x16x32_bf16 v[10:13], v[142:145], v[222:225], v[10:13]
	s_setprio 0
	s_setprio 1
	v_mfma_f32_16x16x32_bf16 v[54:57], v[146:149], v[172:175], v[54:57]
	v_mfma_f32_16x16x32_bf16 v[50:53], v[154:157], v[172:175], v[50:53]
	v_mfma_f32_16x16x32_bf16 v[38:41], v[146:149], v[188:191], v[38:41]
	v_mfma_f32_16x16x32_bf16 v[30:33], v[154:157], v[188:191], v[30:33]
	v_mfma_f32_16x16x32_bf16 v[22:25], v[146:149], v[196:199], v[22:25]
	v_mfma_f32_16x16x32_bf16 v[14:17], v[154:157], v[196:199], v[14:17]
	v_mfma_f32_16x16x32_bf16 v[6:9], v[146:149], v[204:207], v[6:9]
	v_mfma_f32_16x16x32_bf16 v[2:5], v[154:157], v[204:207], v[2:5]
	v_mfma_f32_16x16x32_bf16 v[54:57], v[150:153], v[176:179], v[54:57]
	v_mfma_f32_16x16x32_bf16 v[50:53], v[168:171], v[176:179], v[50:53]
	v_mfma_f32_16x16x32_bf16 v[38:41], v[150:153], v[192:195], v[38:41]
	v_mfma_f32_16x16x32_bf16 v[30:33], v[168:171], v[192:195], v[30:33]
	v_mfma_f32_16x16x32_bf16 v[22:25], v[150:153], v[200:203], v[22:25]
	v_mfma_f32_16x16x32_bf16 v[14:17], v[168:171], v[200:203], v[14:17]
	s_barrier
	v_mfma_f32_16x16x32_bf16 v[6:9], v[150:153], v[222:225], v[6:9]
	v_mfma_f32_16x16x32_bf16 v[2:5], v[168:171], v[222:225], v[2:5]
	s_setprio 0
	s_add_u32 s30, s30, 0x100
	s_addc_u32 s31, s31, 0
	s_add_u32 s42, s42, 0x100
	s_addc_u32 s43, s43, 0
	s_cmp_ge_u32 s59, s48
	s_mov_b32 s34, s59
	s_cbranch_scc0 .LBB0_452
	s_and_b64 vcc, exec, s[24:25]
	s_cbranch_vccz .LBB0_455
	s_barrier

.LBB0_489:
	s_add_u32 s4, s30, 0xfffc0080
	s_addc_u32 s5, s31, -1
	s_add_i32 s6, 0, 0x10000
	s_cmp_eq_u32 s59, 12
	s_cselect_b32 s37, s25, s5
	s_cselect_b32 s36, s66, s4
	s_cselect_b32 s35, s23, s69
	s_cselect_b32 s34, s67, s68
	s_add_i32 s7, 0, 0x14000
	v_add_u32_e32 v156, s6, v146
	v_add_u32_e32 v172, s7, v146
	ds_read_b128 v[140:143], v156
	ds_read_b128 v[148:151], v156 offset:1024
	ds_read_b128 v[152:155], v156 offset:2048
	ds_read_b128 v[156:159], v156 offset:3072
	ds_read_b128 v[160:163], v172
	ds_read_b128 v[164:167], v172 offset:1024
	ds_read_b128 v[168:171], v172 offset:2048
	ds_read_b128 v[172:175], v172 offset:3072
	v_lshl_add_u64 v[208:209], s[30:31], 0, v[136:137]
	s_add_i32 m0, s43, 0xc000
	ds_read_b128 v[176:179], v147
	ds_read_b128 v[180:183], v147 offset:1024
	ds_read_b128 v[184:187], v147 offset:2048
	ds_read_b128 v[188:191], v147 offset:3072
	ds_read_b128 v[192:195], v147 offset:4096
	ds_read_b128 v[196:199], v147 offset:5120
	ds_read_b128 v[200:203], v147 offset:6144
	ds_read_b128 v[204:207], v147 offset:7168
	global_load_lds_dwordx4 v[208:209], off
	v_lshl_add_u64 v[208:209], s[30:31], 0, v[138:139]
	s_add_i32 m0, s43, 0xe000
	s_nop 0
	global_load_lds_dwordx4 v[208:209], off
	s_waitcnt vmcnt(8)
	s_waitcnt lgkmcnt(0)
	s_barrier
	s_setprio 1
	s_waitcnt lgkmcnt(0)
	v_mfma_f32_16x16x32_bf16 v[126:129], v[140:143], v[176:179], v[126:129]
	v_mfma_f32_16x16x32_bf16 v[122:125], v[152:155], v[176:179], v[122:125]
	v_mfma_f32_16x16x32_bf16 v[118:121], v[140:143], v[184:187], v[118:121]
	v_mfma_f32_16x16x32_bf16 v[110:113], v[152:155], v[184:187], v[110:113]
	v_mfma_f32_16x16x32_bf16 v[102:105], v[140:143], v[192:195], v[102:105]
	v_mfma_f32_16x16x32_bf16 v[94:97], v[152:155], v[192:195], v[94:97]
	v_mfma_f32_16x16x32_bf16 v[86:89], v[140:143], v[200:203], v[86:89]
	v_mfma_f32_16x16x32_bf16 v[78:81], v[152:155], v[200:203], v[78:81]
	v_mfma_f32_16x16x32_bf16 v[126:129], v[148:151], v[180:183], v[126:129]
	v_mfma_f32_16x16x32_bf16 v[122:125], v[156:159], v[180:183], v[122:125]
	v_mfma_f32_16x16x32_bf16 v[118:121], v[148:151], v[188:191], v[118:121]
	v_mfma_f32_16x16x32_bf16 v[110:113], v[156:159], v[188:191], v[110:113]
	v_mfma_f32_16x16x32_bf16 v[102:105], v[148:151], v[196:199], v[102:105]
	v_mfma_f32_16x16x32_bf16 v[94:97], v[156:159], v[196:199], v[94:97]
	v_mfma_f32_16x16x32_bf16 v[86:89], v[148:151], v[204:207], v[86:89]
	v_mfma_f32_16x16x32_bf16 v[78:81], v[156:159], v[204:207], v[78:81]
	s_setprio 0
	s_setprio 1
	v_mfma_f32_16x16x32_bf16 v[114:117], v[160:163], v[176:179], v[114:117]
	v_mfma_f32_16x16x32_bf16 v[106:109], v[168:171], v[176:179], v[106:109]
	v_mfma_f32_16x16x32_bf16 v[98:101], v[160:163], v[184:187], v[98:101]
	v_mfma_f32_16x16x32_bf16 v[90:93], v[168:171], v[184:187], v[90:93]
	v_mfma_f32_16x16x32_bf16 v[82:85], v[160:163], v[192:195], v[82:85]
	v_mfma_f32_16x16x32_bf16 v[74:77], v[168:171], v[192:195], v[74:77]
	v_mfma_f32_16x16x32_bf16 v[70:73], v[160:163], v[200:203], v[70:73]
	v_mfma_f32_16x16x32_bf16 v[66:69], v[168:171], v[200:203], v[66:69]
	v_mfma_f32_16x16x32_bf16 v[114:117], v[164:167], v[180:183], v[114:117]
	v_mfma_f32_16x16x32_bf16 v[106:109], v[172:175], v[180:183], v[106:109]
	v_mfma_f32_16x16x32_bf16 v[98:101], v[164:167], v[188:191], v[98:101]
	v_mfma_f32_16x16x32_bf16 v[90:93], v[172:175], v[188:191], v[90:93]
	v_mfma_f32_16x16x32_bf16 v[82:85], v[164:167], v[196:199], v[82:85]
	v_mfma_f32_16x16x32_bf16 v[74:77], v[172:175], v[196:199], v[74:77]
	s_barrier
	v_mfma_f32_16x16x32_bf16 v[70:73], v[164:167], v[204:207], v[70:73]
	v_mfma_f32_16x16x32_bf16 v[66:69], v[172:175], v[204:207], v[66:69]
	s_setprio 0
	s_add_i32 s4, s6, s38
	v_lshl_add_u64 v[208:209], s[34:35], 0, v[0:1]
	s_mov_b32 m0, s4
	ds_read_b128 v[176:179], v147 offset:16384
	ds_read_b128 v[180:183], v147 offset:17408
	ds_read_b128 v[184:187], v147 offset:18432
	ds_read_b128 v[188:191], v147 offset:19456
	ds_read_b128 v[192:195], v147 offset:20480
	ds_read_b128 v[196:199], v147 offset:21504
	ds_read_b128 v[200:203], v147 offset:22528
	ds_read_b128 v[204:207], v147 offset:23552
	global_load_lds_dwordx4 v[208:209], off
	s_add_i32 m0, s4, 0x2000
	s_add_u32 s4, s34, 0x40000
	v_lshl_add_u64 v[222:223], s[34:35], 0, v[132:133]
	s_addc_u32 s5, s35, 0
	s_add_i32 s6, s7, s38
	global_load_lds_dwordx4 v[222:223], off
	v_lshl_add_u64 v[224:225], s[4:5], 0, v[0:1]
	s_mov_b32 m0, s6
	v_lshl_add_u64 v[226:227], s[36:37], 0, v[130:131]
	global_load_lds_dwordx4 v[224:225], off
	v_lshl_add_u64 v[224:225], s[4:5], 0, v[132:133]
	s_add_i32 m0, s6, 0x2000
	s_nop 0
	global_load_lds_dwordx4 v[224:225], off
	v_lshl_add_u64 v[224:225], s[36:37], 0, v[134:135]
	s_mov_b32 m0, s43
	s_nop 0
	global_load_lds_dwordx4 v[224:225], off
	s_mov_b32 m0, s44
	s_nop 0
	global_load_lds_dwordx4 v[226:227], off
	s_waitcnt vmcnt(8)
	s_waitcnt lgkmcnt(0)
	s_barrier
	s_setprio 1
	s_waitcnt lgkmcnt(0)
	v_mfma_f32_16x16x32_bf16 v[62:65], v[140:143], v[176:179], v[62:65]
	v_mfma_f32_16x16x32_bf16 v[58:61], v[152:155], v[176:179], v[58:61]
	v_mfma_f32_16x16x32_bf16 v[54:57], v[140:143], v[184:187], v[54:57]
	v_mfma_f32_16x16x32_bf16 v[46:49], v[152:155], v[184:187], v[46:49]
	v_mfma_f32_16x16x32_bf16 v[38:41], v[140:143], v[192:195], v[38:41]
	v_mfma_f32_16x16x32_bf16 v[30:33], v[152:155], v[192:195], v[30:33]
	v_mfma_f32_16x16x32_bf16 v[22:25], v[140:143], v[200:203], v[22:25]
	v_mfma_f32_16x16x32_bf16 v[14:17], v[152:155], v[200:203], v[14:17]
	v_mfma_f32_16x16x32_bf16 v[62:65], v[148:151], v[180:183], v[62:65]
	v_mfma_f32_16x16x32_bf16 v[58:61], v[156:159], v[180:183], v[58:61]
	v_mfma_f32_16x16x32_bf16 v[54:57], v[148:151], v[188:191], v[54:57]
	v_mfma_f32_16x16x32_bf16 v[46:49], v[156:159], v[188:191], v[46:49]
	v_mfma_f32_16x16x32_bf16 v[38:41], v[148:151], v[196:199], v[38:41]
	v_mfma_f32_16x16x32_bf16 v[30:33], v[156:159], v[196:199], v[30:33]
	v_mfma_f32_16x16x32_bf16 v[22:25], v[148:151], v[204:207], v[22:25]
	v_mfma_f32_16x16x32_bf16 v[14:17], v[156:159], v[204:207], v[14:17]
	s_setprio 0
	s_setprio 1
	v_mfma_f32_16x16x32_bf16 v[50:53], v[160:163], v[176:179], v[50:53]
	v_mfma_f32_16x16x32_bf16 v[42:45], v[168:171], v[176:179], v[42:45]
	v_mfma_f32_16x16x32_bf16 v[34:37], v[160:163], v[184:187], v[34:37]
	v_mfma_f32_16x16x32_bf16 v[26:29], v[168:171], v[184:187], v[26:29]
	v_mfma_f32_16x16x32_bf16 v[18:21], v[160:163], v[192:195], v[18:21]
	v_mfma_f32_16x16x32_bf16 v[10:13], v[168:171], v[192:195], v[10:13]
	v_mfma_f32_16x16x32_bf16 v[6:9], v[160:163], v[200:203], v[6:9]
	v_mfma_f32_16x16x32_bf16 v[2:5], v[168:171], v[200:203], v[2:5]
	v_mfma_f32_16x16x32_bf16 v[50:53], v[164:167], v[180:183], v[50:53]
	v_mfma_f32_16x16x32_bf16 v[42:45], v[172:175], v[180:183], v[42:45]
	v_mfma_f32_16x16x32_bf16 v[34:37], v[164:167], v[188:191], v[34:37]
	v_mfma_f32_16x16x32_bf16 v[26:29], v[172:175], v[188:191], v[26:29]
	v_mfma_f32_16x16x32_bf16 v[18:21], v[164:167], v[196:199], v[18:21]
	v_mfma_f32_16x16x32_bf16 v[10:13], v[172:175], v[196:199], v[10:13]
	s_barrier
	v_mfma_f32_16x16x32_bf16 v[6:9], v[164:167], v[204:207], v[6:9]
	v_mfma_f32_16x16x32_bf16 v[2:5], v[172:175], v[204:207], v[2:5]
	s_setprio 0
	s_add_i32 s6, 0, 0x18000
	s_add_i32 s7, 0, 0x1c000
	v_add_u32_e32 v156, s6, v146
	v_add_u32_e32 v172, s7, v146
	ds_read_b128 v[140:143], v156
	ds_read_b128 v[148:151], v156 offset:1024
	ds_read_b128 v[152:155], v156 offset:2048
	ds_read_b128 v[156:159], v156 offset:3072
	ds_read_b128 v[160:163], v172
	ds_read_b128 v[164:167], v172 offset:1024
	ds_read_b128 v[168:171], v172 offset:2048
	ds_read_b128 v[172:175], v172 offset:3072
	s_add_u32 s4, s36, 0x40000
	s_addc_u32 s5, s37, 0
	s_mov_b32 m0, s45
	v_lshl_add_u64 v[228:229], s[4:5], 0, v[134:135]
	ds_read_b128 v[176:179], v147 offset:32768
	ds_read_b128 v[180:183], v147 offset:33792
	ds_read_b128 v[184:187], v147 offset:34816
	ds_read_b128 v[188:191], v147 offset:35840
	ds_read_b128 v[192:195], v147 offset:36864
	ds_read_b128 v[196:199], v147 offset:37888
	ds_read_b128 v[200:203], v147 offset:38912
	ds_read_b128 v[204:207], v147 offset:39936
	global_load_lds_dwordx4 v[228:229], off
	v_lshl_add_u64 v[228:229], s[4:5], 0, v[130:131]
	s_mov_b32 m0, s46
	s_nop 0
	global_load_lds_dwordx4 v[228:229], off
	s_waitcnt vmcnt(8)
	s_waitcnt lgkmcnt(0)
	s_barrier
	s_setprio 1
	s_waitcnt lgkmcnt(0)
	v_mfma_f32_16x16x32_bf16 v[126:129], v[140:143], v[176:179], v[126:129]
	v_mfma_f32_16x16x32_bf16 v[122:125], v[152:155], v[176:179], v[122:125]
	v_mfma_f32_16x16x32_bf16 v[118:121], v[140:143], v[184:187], v[118:121]
	v_mfma_f32_16x16x32_bf16 v[110:113], v[152:155], v[184:187], v[110:113]
	v_mfma_f32_16x16x32_bf16 v[102:105], v[140:143], v[192:195], v[102:105]
	v_mfma_f32_16x16x32_bf16 v[94:97], v[152:155], v[192:195], v[94:97]
	v_mfma_f32_16x16x32_bf16 v[86:89], v[140:143], v[200:203], v[86:89]
	v_mfma_f32_16x16x32_bf16 v[78:81], v[152:155], v[200:203], v[78:81]
	v_mfma_f32_16x16x32_bf16 v[126:129], v[148:151], v[180:183], v[126:129]
	v_mfma_f32_16x16x32_bf16 v[122:125], v[156:159], v[180:183], v[122:125]
	v_mfma_f32_16x16x32_bf16 v[118:121], v[148:151], v[188:191], v[118:121]
	v_mfma_f32_16x16x32_bf16 v[110:113], v[156:159], v[188:191], v[110:113]
	v_mfma_f32_16x16x32_bf16 v[102:105], v[148:151], v[196:199], v[102:105]
	v_mfma_f32_16x16x32_bf16 v[94:97], v[156:159], v[196:199], v[94:97]
	v_mfma_f32_16x16x32_bf16 v[86:89], v[148:151], v[204:207], v[86:89]
	v_mfma_f32_16x16x32_bf16 v[78:81], v[156:159], v[204:207], v[78:81]
	s_setprio 0
	s_setprio 1
	v_mfma_f32_16x16x32_bf16 v[114:117], v[160:163], v[176:179], v[114:117]
	v_mfma_f32_16x16x32_bf16 v[106:109], v[168:171], v[176:179], v[106:109]
	v_mfma_f32_16x16x32_bf16 v[98:101], v[160:163], v[184:187], v[98:101]
	v_mfma_f32_16x16x32_bf16 v[90:93], v[168:171], v[184:187], v[90:93]
	v_mfma_f32_16x16x32_bf16 v[82:85], v[160:163], v[192:195], v[82:85]
	v_mfma_f32_16x16x32_bf16 v[74:77], v[168:171], v[192:195], v[74:77]
	v_mfma_f32_16x16x32_bf16 v[70:73], v[160:163], v[200:203], v[70:73]
	v_mfma_f32_16x16x32_bf16 v[66:69], v[168:171], v[200:203], v[66:69]
	v_mfma_f32_16x16x32_bf16 v[114:117], v[164:167], v[180:183], v[114:117]
	v_mfma_f32_16x16x32_bf16 v[106:109], v[172:175], v[180:183], v[106:109]
	v_mfma_f32_16x16x32_bf16 v[98:101], v[164:167], v[188:191], v[98:101]
	v_mfma_f32_16x16x32_bf16 v[90:93], v[172:175], v[188:191], v[90:93]
	v_mfma_f32_16x16x32_bf16 v[82:85], v[164:167], v[196:199], v[82:85]
	v_mfma_f32_16x16x32_bf16 v[74:77], v[172:175], v[196:199], v[74:77]
	s_barrier
	v_mfma_f32_16x16x32_bf16 v[70:73], v[164:167], v[204:207], v[70:73]
	v_mfma_f32_16x16x32_bf16 v[66:69], v[172:175], v[204:207], v[66:69]
	s_setprio 0
	s_add_i32 s4, s6, s38
	v_lshl_add_u64 v[208:209], v[208:209], 0, s[82:83]
	s_mov_b32 m0, s4
	ds_read_b128 v[176:179], v147 offset:49152
	ds_read_b128 v[180:183], v147 offset:50176
	ds_read_b128 v[184:187], v147 offset:51200
	ds_read_b128 v[188:191], v147 offset:52224
	ds_read_b128 v[192:195], v147 offset:53248
	ds_read_b128 v[196:199], v147 offset:54272
	ds_read_b128 v[200:203], v147 offset:55296
	ds_read_b128 v[204:207], v147 offset:56320
	global_load_lds_dwordx4 v[208:209], off
	s_add_i32 m0, s4, 0x2000
	s_add_u32 s4, s34, 0x40080
	v_lshl_add_u64 v[208:209], v[222:223], 0, s[82:83]
	s_addc_u32 s5, s35, 0
	s_add_i32 s6, s7, s38
	global_load_lds_dwordx4 v[208:209], off
	v_lshl_add_u64 v[208:209], s[4:5], 0, v[0:1]
	s_mov_b32 m0, s6
	s_nop 0
	global_load_lds_dwordx4 v[208:209], off
	v_lshl_add_u64 v[208:209], s[4:5], 0, v[132:133]
	s_add_i32 m0, s6, 0x2000
	s_nop 0
	global_load_lds_dwordx4 v[208:209], off
	v_lshl_add_u64 v[208:209], v[224:225], 0, s[82:83]
	s_mov_b32 m0, s49
	s_nop 0
	global_load_lds_dwordx4 v[208:209], off
	v_lshl_add_u64 v[208:209], v[226:227], 0, s[82:83]
	s_mov_b32 m0, s50
	s_nop 0
	global_load_lds_dwordx4 v[208:209], off
	s_waitcnt vmcnt(8)
	s_waitcnt lgkmcnt(0)
	s_barrier
	s_setprio 1
	s_waitcnt lgkmcnt(0)
	v_mfma_f32_16x16x32_bf16 v[62:65], v[140:143], v[176:179], v[62:65]
	v_mfma_f32_16x16x32_bf16 v[58:61], v[152:155], v[176:179], v[58:61]
	v_mfma_f32_16x16x32_bf16 v[54:57], v[140:143], v[184:187], v[54:57]
	v_mfma_f32_16x16x32_bf16 v[46:49], v[152:155], v[184:187], v[46:49]
	v_mfma_f32_16x16x32_bf16 v[38:41], v[140:143], v[192:195], v[38:41]
	v_mfma_f32_16x16x32_bf16 v[30:33], v[152:155], v[192:195], v[30:33]
	v_mfma_f32_16x16x32_bf16 v[22:25], v[140:143], v[200:203], v[22:25]
	v_mfma_f32_16x16x32_bf16 v[14:17], v[152:155], v[200:203], v[14:17]
	v_mfma_f32_16x16x32_bf16 v[62:65], v[148:151], v[180:183], v[62:65]
	v_mfma_f32_16x16x32_bf16 v[58:61], v[156:159], v[180:183], v[58:61]
	v_mfma_f32_16x16x32_bf16 v[54:57], v[148:151], v[188:191], v[54:57]
	v_mfma_f32_16x16x32_bf16 v[46:49], v[156:159], v[188:191], v[46:49]
	v_mfma_f32_16x16x32_bf16 v[38:41], v[148:151], v[196:199], v[38:41]
	v_mfma_f32_16x16x32_bf16 v[30:33], v[156:159], v[196:199], v[30:33]
	v_mfma_f32_16x16x32_bf16 v[22:25], v[148:151], v[204:207], v[22:25]
	v_mfma_f32_16x16x32_bf16 v[14:17], v[156:159], v[204:207], v[14:17]
	s_setprio 0
	s_setprio 1
	v_mfma_f32_16x16x32_bf16 v[50:53], v[160:163], v[176:179], v[50:53]
	v_mfma_f32_16x16x32_bf16 v[42:45], v[168:171], v[176:179], v[42:45]
	v_mfma_f32_16x16x32_bf16 v[34:37], v[160:163], v[184:187], v[34:37]
	v_mfma_f32_16x16x32_bf16 v[26:29], v[168:171], v[184:187], v[26:29]
	v_mfma_f32_16x16x32_bf16 v[18:21], v[160:163], v[192:195], v[18:21]
	v_mfma_f32_16x16x32_bf16 v[10:13], v[168:171], v[192:195], v[10:13]
	v_mfma_f32_16x16x32_bf16 v[6:9], v[160:163], v[200:203], v[6:9]
	v_mfma_f32_16x16x32_bf16 v[2:5], v[168:171], v[200:203], v[2:5]
	v_mfma_f32_16x16x32_bf16 v[50:53], v[164:167], v[180:183], v[50:53]
	v_mfma_f32_16x16x32_bf16 v[42:45], v[172:175], v[180:183], v[42:45]
	v_mfma_f32_16x16x32_bf16 v[34:37], v[164:167], v[188:191], v[34:37]
	v_mfma_f32_16x16x32_bf16 v[26:29], v[172:175], v[188:191], v[26:29]
	v_mfma_f32_16x16x32_bf16 v[18:21], v[164:167], v[196:199], v[18:21]
	v_mfma_f32_16x16x32_bf16 v[10:13], v[172:175], v[196:199], v[10:13]
	s_barrier
	v_mfma_f32_16x16x32_bf16 v[6:9], v[164:167], v[204:207], v[6:9]
	v_mfma_f32_16x16x32_bf16 v[2:5], v[172:175], v[204:207], v[2:5]
	s_setprio 0
	s_add_i32 s59, s59, 2
	s_add_u32 s30, s30, 0x100
	s_addc_u32 s31, s31, 0
	s_add_u32 s68, s68, 0x100
	s_addc_u32 s69, s69, 0
	s_cmp_gt_u32 s59, 13
	s_cbranch_scc0 .LBB0_489
	s_and_b64 vcc, exec, s[20:21]
	s_cbranch_vccz .LBB0_492
	s_barrier
